# D6: NSA window-branch tile loop also gets the piecewise next-tile staging between the PV MFMAs
# speedup vs baseline: 1.0177x; 1.0024x over previous
.LBB0_927:
	s_add_i32 s1, s0, 1
	s_cmp_lg_u32 s0, 2
	s_cselect_b32 s15, s1, 0
	s_cmp_ge_i32 s6, s8
	s_cselect_b64 s[4:5], -1, 0
.LBB0_931:
	s_cmp_le_i32 s14, s7
	s_cselect_b64 s[16:17], -1, 0
	s_add_i32 s1, s14, 63
	s_cmp_ge_i32 s1, s9
	s_cselect_b64 s[22:23], -1, 0
	s_and_b64 s[16:17], s[16:17], s[22:23]
	s_andn2_b64 vcc, exec, s[16:17]
	s_waitcnt lgkmcnt(0)
	s_barrier
	s_cbranch_vccnz .Ld6_inactive
	s_mul_i32 s16, s0, 0x4a00
	v_add3_u32 v142, s16, v182, v130
	ds_read_b128 v[50:53], v142
	ds_read_b128 v[138:141], v142 offset:4608
	ds_read_b128 v[236:239], v142 offset:32
	ds_read_b128 v[240:243], v142 offset:4640
	ds_read_b128 v[244:247], v142 offset:64
	ds_read_b128 v[248:251], v142 offset:4672
	v_cmp_le_i32_e32 vcc, s1, v128
	v_cmp_ge_i32_e64 s[0:1], s14, v137
	s_and_b64 s[0:1], vcc, s[0:1]
	s_waitcnt lgkmcnt(5)
	v_mfma_f32_32x32x16_bf16 v[66:81], v[50:53], v[82:85], v[34:49]
	s_waitcnt lgkmcnt(4)
	v_mfma_f32_32x32x16_bf16 v[50:65], v[138:141], v[82:85], v[34:49]
	ds_read_b128 v[138:141], v142 offset:96
	s_waitcnt lgkmcnt(4)
	v_mfma_f32_32x32x16_bf16 v[66:81], v[236:239], v[86:89], v[66:81]
	ds_read_b128 v[236:239], v142 offset:4704
	s_waitcnt lgkmcnt(4)
	v_mfma_f32_32x32x16_bf16 v[50:65], v[240:243], v[86:89], v[50:65]
	s_waitcnt lgkmcnt(3)
	v_mfma_f32_32x32x16_bf16 v[66:81], v[244:247], v[90:93], v[66:81]
	s_waitcnt lgkmcnt(2)
	v_mfma_f32_32x32x16_bf16 v[50:65], v[248:251], v[90:93], v[50:65]
	s_waitcnt lgkmcnt(1)
	v_mfma_f32_32x32x16_bf16 v[66:81], v[138:141], v[94:97], v[66:81]
	v_cndmask_b32_e64 v142, 0, 1, s[0:1]
	v_cmp_ne_u32_e32 vcc, 0, v142
	s_cmp_eq_u64 vcc, exec
	s_waitcnt lgkmcnt(0)
	v_mfma_f32_32x32x16_bf16 v[50:65], v[236:239], v[94:97], v[50:65]
	s_cbranch_scc1 .LBB0_936
	v_add_u32_e32 v138, s14, v125
	v_cmp_gt_i32_e32 vcc, v138, v128
	v_cmp_lt_i32_e64 s[0:1], v138, v137
	s_or_b64 vcc, vcc, s[0:1]
	v_add_u32_e32 v139, 1, v138
	v_cndmask_b32_e32 v66, v66, v169, vcc
	v_cmp_ge_i32_e32 vcc, v138, v128
	v_cmp_lt_i32_e64 s[0:1], v139, v137
	s_or_b64 vcc, vcc, s[0:1]
	v_add_u32_e32 v139, 2, v138
	v_cndmask_b32_e32 v67, v67, v169, vcc
	v_cmp_gt_i32_e32 vcc, v139, v128
	v_cmp_lt_i32_e64 s[0:1], v139, v137
	s_or_b64 vcc, vcc, s[0:1]
	v_add_u32_e32 v139, 3, v138
	v_cndmask_b32_e32 v68, v68, v169, vcc
	v_cmp_gt_i32_e32 vcc, v139, v128
	v_cmp_lt_i32_e64 s[0:1], v139, v137
	s_or_b64 vcc, vcc, s[0:1]
	v_add_u32_e32 v139, 8, v138
	v_cndmask_b32_e32 v69, v69, v169, vcc
	v_cmp_gt_i32_e32 vcc, v139, v128
	v_cmp_lt_i32_e64 s[0:1], v139, v137
	s_or_b64 vcc, vcc, s[0:1]
	v_add_u32_e32 v139, 9, v138
	v_cndmask_b32_e32 v70, v70, v169, vcc
	v_cmp_gt_i32_e32 vcc, v139, v128
	v_cmp_lt_i32_e64 s[0:1], v139, v137
	s_or_b64 vcc, vcc, s[0:1]
	v_add_u32_e32 v139, 10, v138
	v_cndmask_b32_e32 v71, v71, v169, vcc
	v_cmp_gt_i32_e32 vcc, v139, v128
	v_cmp_lt_i32_e64 s[0:1], v139, v137
	s_or_b64 vcc, vcc, s[0:1]
	v_add_u32_e32 v139, 11, v138
	v_cndmask_b32_e32 v72, v72, v169, vcc
	v_cmp_gt_i32_e32 vcc, v139, v128
	v_cmp_lt_i32_e64 s[0:1], v139, v137
	s_or_b64 vcc, vcc, s[0:1]
	v_add_u32_e32 v139, 16, v138
	v_cndmask_b32_e32 v73, v73, v169, vcc
	v_cmp_gt_i32_e32 vcc, v139, v128
	v_cmp_lt_i32_e64 s[0:1], v139, v137
	s_or_b64 vcc, vcc, s[0:1]
	v_add_u32_e32 v139, 17, v138
	v_cndmask_b32_e32 v74, v74, v169, vcc
	v_cmp_gt_i32_e32 vcc, v139, v128
	v_cmp_lt_i32_e64 s[0:1], v139, v137
	s_or_b64 vcc, vcc, s[0:1]
	v_add_u32_e32 v139, 18, v138
	v_cndmask_b32_e32 v75, v75, v169, vcc
	v_cmp_gt_i32_e32 vcc, v139, v128
	v_cmp_lt_i32_e64 s[0:1], v139, v137
	s_or_b64 vcc, vcc, s[0:1]
	v_add_u32_e32 v139, 19, v138
	v_cndmask_b32_e32 v76, v76, v169, vcc
	v_cmp_gt_i32_e32 vcc, v139, v128
	v_cmp_lt_i32_e64 s[0:1], v139, v137
	s_or_b64 vcc, vcc, s[0:1]
	v_add_u32_e32 v139, 24, v138
	v_cndmask_b32_e32 v77, v77, v169, vcc
	v_cmp_gt_i32_e32 vcc, v139, v128
	v_cmp_lt_i32_e64 s[0:1], v139, v137
	s_or_b64 vcc, vcc, s[0:1]
	v_add_u32_e32 v139, 25, v138
	v_cndmask_b32_e32 v78, v78, v169, vcc
	v_cmp_gt_i32_e32 vcc, v139, v128
	v_cmp_lt_i32_e64 s[0:1], v139, v137
	s_or_b64 vcc, vcc, s[0:1]
	v_add_u32_e32 v139, 26, v138
	v_cndmask_b32_e32 v79, v79, v169, vcc
	v_cmp_gt_i32_e32 vcc, v139, v128
	v_cmp_lt_i32_e64 s[0:1], v139, v137
	s_or_b64 vcc, vcc, s[0:1]
	v_add_u32_e32 v139, 27, v138
	v_cndmask_b32_e32 v80, v80, v169, vcc
	v_cmp_gt_i32_e32 vcc, v139, v128
	v_cmp_lt_i32_e64 s[0:1], v139, v137
	s_or_b64 vcc, vcc, s[0:1]
	v_add_u32_e32 v139, 32, v138
	v_cndmask_b32_e32 v81, v81, v169, vcc
	v_cmp_gt_i32_e32 vcc, v139, v128
	v_cmp_lt_i32_e64 s[0:1], v139, v137
	s_or_b64 vcc, vcc, s[0:1]
	v_add_u32_e32 v139, 33, v138
	v_cndmask_b32_e32 v50, v50, v169, vcc
	v_cmp_gt_i32_e32 vcc, v139, v128
	v_cmp_lt_i32_e64 s[0:1], v139, v137
	s_or_b64 vcc, vcc, s[0:1]
	v_add_u32_e32 v139, 34, v138
	v_cndmask_b32_e32 v51, v51, v169, vcc
	v_cmp_gt_i32_e32 vcc, v139, v128
	v_cmp_lt_i32_e64 s[0:1], v139, v137
	s_or_b64 vcc, vcc, s[0:1]
	v_add_u32_e32 v139, 35, v138
	v_cndmask_b32_e32 v52, v52, v169, vcc
	v_cmp_gt_i32_e32 vcc, v139, v128
	v_cmp_lt_i32_e64 s[0:1], v139, v137
	s_or_b64 vcc, vcc, s[0:1]
	v_add_u32_e32 v139, 40, v138
	v_cndmask_b32_e32 v53, v53, v169, vcc
	v_cmp_gt_i32_e32 vcc, v139, v128
	v_cmp_lt_i32_e64 s[0:1], v139, v137
	s_or_b64 vcc, vcc, s[0:1]
	v_add_u32_e32 v139, 41, v138
	v_cndmask_b32_e32 v54, v54, v169, vcc
	v_cmp_gt_i32_e32 vcc, v139, v128
	v_cmp_lt_i32_e64 s[0:1], v139, v137
	s_or_b64 vcc, vcc, s[0:1]
	v_add_u32_e32 v139, 42, v138
	v_cndmask_b32_e32 v55, v55, v169, vcc
	v_cmp_gt_i32_e32 vcc, v139, v128
	v_cmp_lt_i32_e64 s[0:1], v139, v137
	s_or_b64 vcc, vcc, s[0:1]
	v_add_u32_e32 v139, 43, v138
	v_cndmask_b32_e32 v56, v56, v169, vcc
	v_cmp_gt_i32_e32 vcc, v139, v128
	v_cmp_lt_i32_e64 s[0:1], v139, v137
	s_or_b64 vcc, vcc, s[0:1]
	v_add_u32_e32 v139, 48, v138
	v_cndmask_b32_e32 v57, v57, v169, vcc
	v_cmp_gt_i32_e32 vcc, v139, v128
	v_cmp_lt_i32_e64 s[0:1], v139, v137
	s_or_b64 vcc, vcc, s[0:1]
	v_add_u32_e32 v139, 49, v138
	v_cndmask_b32_e32 v58, v58, v169, vcc
	v_cmp_gt_i32_e32 vcc, v139, v128
	v_cmp_lt_i32_e64 s[0:1], v139, v137
	s_or_b64 vcc, vcc, s[0:1]
	v_add_u32_e32 v139, 50, v138
	v_cndmask_b32_e32 v59, v59, v169, vcc
	v_cmp_gt_i32_e32 vcc, v139, v128
	v_cmp_lt_i32_e64 s[0:1], v139, v137
	s_or_b64 vcc, vcc, s[0:1]
	v_add_u32_e32 v139, 51, v138
	v_cndmask_b32_e32 v60, v60, v169, vcc
	v_cmp_gt_i32_e32 vcc, v139, v128
	v_cmp_lt_i32_e64 s[0:1], v139, v137
	s_or_b64 vcc, vcc, s[0:1]
	v_add_u32_e32 v139, 56, v138
	v_cndmask_b32_e32 v61, v61, v169, vcc
	v_cmp_gt_i32_e32 vcc, v139, v128
	v_cmp_lt_i32_e64 s[0:1], v139, v137
	s_or_b64 vcc, vcc, s[0:1]
	v_add_u32_e32 v139, 57, v138
	v_cndmask_b32_e32 v62, v62, v169, vcc
	v_cmp_gt_i32_e32 vcc, v139, v128
	v_cmp_lt_i32_e64 s[0:1], v139, v137
	s_or_b64 vcc, vcc, s[0:1]
	v_add_u32_e32 v139, 58, v138
	v_cndmask_b32_e32 v63, v63, v169, vcc
	v_cmp_gt_i32_e32 vcc, v139, v128
	v_cmp_lt_i32_e64 s[0:1], v139, v137
	s_or_b64 vcc, vcc, s[0:1]
	v_add_u32_e32 v138, 59, v138
	v_cndmask_b32_e32 v64, v64, v169, vcc
	v_cmp_gt_i32_e32 vcc, v138, v128
	v_cmp_lt_i32_e64 s[0:1], v138, v137
	s_or_b64 s[22:23], vcc, s[0:1]
	s_and_saveexec_b64 s[0:1], s[22:23]
	v_mov_b32_e32 v65, 0xf149f2ca
	s_or_b64 exec, exec, s[0:1]
.LBB0_936:
	s_nop 4
	v_exp_f32_e32 v66, v66
	v_exp_f32_e32 v67, v67
	v_exp_f32_e32 v68, v68
	v_exp_f32_e32 v69, v69
	v_add_f32_e32 v138, 0, v66
	v_exp_f32_e32 v70, v70
	v_add_f32_e32 v138, v67, v138
	v_exp_f32_e32 v71, v71
	v_add_f32_e32 v138, v68, v138
	v_exp_f32_e32 v72, v72
	v_add_f32_e32 v138, v69, v138
	v_exp_f32_e32 v73, v73
	v_add_f32_e32 v138, v70, v138
	v_exp_f32_e32 v74, v74
	v_add_f32_e32 v138, v71, v138
	v_exp_f32_e32 v75, v75
	v_add_f32_e32 v138, v72, v138
	v_exp_f32_e32 v76, v76
	v_add_f32_e32 v138, v73, v138
	v_exp_f32_e32 v77, v77
	v_add_f32_e32 v138, v74, v138
	v_exp_f32_e32 v78, v78
	v_add_f32_e32 v138, v75, v138
	v_exp_f32_e32 v79, v79
	v_add_f32_e32 v138, v76, v138
	v_exp_f32_e32 v80, v80
	v_add_f32_e32 v138, v77, v138
	v_exp_f32_e32 v81, v81
	v_add_f32_e32 v138, v78, v138
	v_exp_f32_e32 v139, v50
	v_add_f32_e32 v138, v79, v138
	v_add_f32_e32 v138, v80, v138
	v_add_f32_e32 v138, v81, v138
	v_add_f32_e32 v50, v139, v138
	v_exp_f32_e32 v138, v52
	v_cvt_pk_bf16_f32 v52, v66, v67
	v_add3_u32 v66, s16, v181, v187
	v_add_u32_e32 v67, 0x2000, v66
	v_exp_f32_e32 v143, v56
	v_exp_f32_e32 v144, v57
	v_exp_f32_e32 v145, v58
	v_exp_f32_e32 v147, v59
	v_exp_f32_e32 v148, v60
	v_exp_f32_e32 v149, v61
	v_exp_f32_e32 v150, v62
	v_exp_f32_e32 v151, v63
	ds_read2_b64 v[56:59], v67 offset0:128 offset1:130
	ds_read2_b64 v[60:63], v67 offset0:132 offset1:134
	v_exp_f32_e32 v140, v53
	v_exp_f32_e32 v141, v54
	v_exp_f32_e32 v142, v55
	v_cvt_pk_bf16_f32 v53, v68, v69
	v_cvt_pk_bf16_f32 v54, v70, v71
	v_cvt_pk_bf16_f32 v55, v72, v73
	v_add_u32_e32 v66, 0x3000, v66
	v_exp_f32_e32 v51, v51
	s_waitcnt lgkmcnt(1)
	v_mfma_f32_32x32x16_bf16 v[18:33], v[56:59], v[52:55], v[18:33]
	s_mul_i32 s22, s15, 0x4a00
	v_or_b32_e32 v252, s22, v129
	v_add_u32_e32 v253, v252, v131
	s_waitcnt vmcnt(3)
	ds_write_b128 v253, v[98:101]
	global_load_dwordx4 v[98:101], v228, s[12:13]
	ds_read2_b64 v[56:59], v66 offset0:160 offset1:162
	v_exp_f32_e32 v64, v64
	v_exp_f32_e32 v65, v65
	v_add_f32_e32 v50, v51, v50
	v_add_f32_e32 v50, v138, v50
	v_add_f32_e32 v50, v140, v50
	v_add_f32_e32 v50, v141, v50
	s_waitcnt lgkmcnt(0)
	v_mfma_f32_32x32x16_bf16 v[2:17], v[56:59], v[52:55], v[2:17]
	ds_read2_b64 v[56:59], v66 offset0:164 offset1:166
	v_cvt_pk_bf16_f32 v52, v74, v75
	v_cvt_pk_bf16_f32 v53, v76, v77
	v_cvt_pk_bf16_f32 v54, v78, v79
	v_cvt_pk_bf16_f32 v55, v80, v81
	v_add_f32_e32 v50, v142, v50
	v_add_f32_e32 v50, v143, v50
	s_waitcnt lgkmcnt(0)
	v_mfma_f32_32x32x16_bf16 v[2:17], v[56:59], v[52:55], v[2:17]
	v_add3_u32 v253, v252, v185, s33
	s_waitcnt vmcnt(2)
	ds_write2_b64 v253, v[102:103], v[104:105] offset1:1
	global_load_dwordx4 v[102:105], v230, s[24:25]
	ds_read2_b64 v[56:59], v67 offset0:136 offset1:138
	v_add_f32_e32 v50, v144, v50
	v_add_f32_e32 v50, v145, v50
	v_add_f32_e32 v50, v147, v50
	v_add_f32_e32 v50, v148, v50
	v_add_f32_e32 v50, v149, v50
	v_add_f32_e32 v50, v150, v50
	v_mfma_f32_32x32x16_bf16 v[18:33], v[60:63], v[52:55], v[18:33]
	v_cvt_pk_bf16_f32 v52, v139, v51
	v_cvt_pk_bf16_f32 v53, v138, v140
	v_cvt_pk_bf16_f32 v54, v141, v142
	v_cvt_pk_bf16_f32 v55, v143, v144
	v_add_f32_e32 v50, v151, v50
	v_add_f32_e32 v50, v64, v50
	v_add_f32_e32 v50, v65, v50
	s_waitcnt lgkmcnt(0)
	v_mfma_f32_32x32x16_bf16 v[18:33], v[56:59], v[52:55], v[18:33]
	v_add_u32_e32 v253, v252, v180
	s_waitcnt vmcnt(3)
	ds_write_b128 v253, v[106:109]
	global_load_dwordx4 v[106:109], v229, s[12:13]
	ds_read2_b64 v[56:59], v66 offset0:168 offset1:170
	v_add_f32_e32 v136, v136, v50
	v_cmp_lt_f32_e32 vcc, s20, v50
	s_waitcnt lgkmcnt(0)
	v_mfma_f32_32x32x16_bf16 v[2:17], v[56:59], v[52:55], v[2:17]
	ds_read2_b64 v[56:59], v67 offset0:140 offset1:142
	v_cvt_pk_bf16_f32 v52, v145, v147
	v_cvt_pk_bf16_f32 v53, v148, v149
	v_cvt_pk_bf16_f32 v54, v150, v151
	v_cvt_pk_bf16_f32 v55, v64, v65
	s_waitcnt lgkmcnt(0)
	s_nop 0
	v_mfma_f32_32x32x16_bf16 v[18:33], v[56:59], v[52:55], v[18:33]
	v_add3_u32 v253, v252, v186, s33
	s_waitcnt vmcnt(3)
	ds_write2_b64 v253, v[110:111], v[112:113] offset1:1
	global_load_dwordx4 v[110:113], v231, s[24:25]
	s_add_u32 s12, s12, 0x2000
	s_addc_u32 s13, s13, 0
	s_add_u32 s24, s24, 0x80
	s_addc_u32 s25, s25, 0
	ds_read2_b64 v[56:59], v66 offset0:172 offset1:174
	s_waitcnt lgkmcnt(0)
	v_mfma_f32_32x32x16_bf16 v[2:17], v[56:59], v[52:55], v[2:17]
	s_cbranch_vccz .LBB0_938
	v_mov_b32_e32 v34, v50
	s_nop 1
	v_permlane32_swap_b32_e32 v50, v34
	v_add_f32_e32 v34, v50, v34
	v_log_f32_e32 v35, v34
	v_cmp_lt_f32_e32 vcc, s20, v34
	s_nop 1
	v_cndmask_b32_e32 v35, 0, v35, vcc
	v_exp_f32_e64 v34, -v35
	v_add_f32_e32 v0, v0, v35
	v_xor_b32_e32 v49, 0x80000000, v0
	v_mov_b32_e32 v48, v49
	v_mul_f32_e32 v136, v136, v34
	v_pk_mul_f32 v[32:33], v[32:33], v[34:35] op_sel_hi:[1,0]
	v_pk_mul_f32 v[30:31], v[30:31], v[34:35] op_sel_hi:[1,0]
	v_pk_mul_f32 v[28:29], v[28:29], v[34:35] op_sel_hi:[1,0]
	v_pk_mul_f32 v[26:27], v[26:27], v[34:35] op_sel_hi:[1,0]
	v_pk_mul_f32 v[24:25], v[24:25], v[34:35] op_sel_hi:[1,0]
	v_pk_mul_f32 v[22:23], v[22:23], v[34:35] op_sel_hi:[1,0]
	v_pk_mul_f32 v[20:21], v[20:21], v[34:35] op_sel_hi:[1,0]
	v_pk_mul_f32 v[18:19], v[18:19], v[34:35] op_sel_hi:[1,0]
	v_pk_mul_f32 v[16:17], v[16:17], v[34:35] op_sel_hi:[1,0]
	v_pk_mul_f32 v[14:15], v[14:15], v[34:35] op_sel_hi:[1,0]
	v_pk_mul_f32 v[12:13], v[12:13], v[34:35] op_sel_hi:[1,0]
	v_pk_mul_f32 v[10:11], v[10:11], v[34:35] op_sel_hi:[1,0]
	v_pk_mul_f32 v[8:9], v[8:9], v[34:35] op_sel_hi:[1,0]
	v_pk_mul_f32 v[6:7], v[6:7], v[34:35] op_sel_hi:[1,0]
	v_pk_mul_f32 v[4:5], v[4:5], v[34:35] op_sel_hi:[1,0]
	v_pk_mul_f32 v[2:3], v[2:3], v[34:35] op_sel_hi:[1,0]
	v_mov_b32_e32 v47, v49
	v_mov_b32_e32 v46, v49
	v_mov_b32_e32 v45, v49
	v_mov_b32_e32 v44, v49
	v_mov_b32_e32 v43, v49
	v_mov_b32_e32 v42, v49
	v_mov_b32_e32 v41, v49
	v_mov_b32_e32 v40, v49
	v_mov_b32_e32 v39, v49
	v_mov_b32_e32 v38, v49
	v_mov_b32_e32 v37, v49
	v_mov_b32_e32 v36, v49
	v_mov_b32_e32 v35, v49
	v_mov_b32_e32 v34, v49
	s_branch .LBB0_938
.Ld6_inactive:
	s_mul_i32 s22, s15, 0x4a00
	v_or_b32_e32 v252, s22, v129
	v_add_u32_e32 v253, v252, v131
	s_waitcnt vmcnt(3)
	ds_write_b128 v253, v[98:101]
	global_load_dwordx4 v[98:101], v228, s[12:13]
	v_add3_u32 v253, v252, v185, s33
	s_waitcnt vmcnt(2)
	ds_write2_b64 v253, v[102:103], v[104:105] offset1:1
	global_load_dwordx4 v[102:105], v230, s[24:25]
	v_add_u32_e32 v253, v252, v180
	s_waitcnt vmcnt(3)
	ds_write_b128 v253, v[106:109]
	global_load_dwordx4 v[106:109], v229, s[12:13]
	v_add3_u32 v253, v252, v186, s33
	s_waitcnt vmcnt(3)
	ds_write2_b64 v253, v[110:111], v[112:113] offset1:1
	global_load_dwordx4 v[110:113], v231, s[24:25]
	s_add_u32 s12, s12, 0x2000
	s_addc_u32 s13, s13, 0
	s_add_u32 s24, s24, 0x80
	s_addc_u32 s25, s25, 0
.LBB0_938:
	s_add_i32 s6, s6, 1
	s_andn2_b64 vcc, exec, s[4:5]
	s_add_i32 s14, s14, 64
	s_cbranch_vccz .Ld6_exit
	s_mov_b32 s0, s15
	s_branch .LBB0_927
.Ld6_exit:
	s_waitcnt vmcnt(0)
	s_branch .LBB0_943
.LBB0_940:
	s_lshl_b32 s14, s6, 6
	v_add_u32_e32 v6, s14, v134
	v_ashrrev_i32_e32 v7, 31, v6
	s_ashr_i32 s15, s14, 31
	v_lshlrev_b64 v[6:7], 7, v[6:7]
	v_lshl_add_u64 v[6:7], s[0:1], 0, v[6:7]
	s_lshl_b64 s[16:17], s[14:15], 1
	v_lshl_add_u64 v[6:7], v[6:7], 0, v[0:1]
	v_lshl_add_u64 v[8:9], v[2:3], 0, s[16:17]
	v_lshl_add_u64 v[8:9], v[8:9], 0, v[0:1]
	global_load_dwordx4 v[98:101], v[6:7], off
	global_load_dwordx4 v[102:105], v[8:9], off
	v_add_u32_e32 v6, s14, v132
	v_ashrrev_i32_e32 v7, 31, v6
	v_lshlrev_b64 v[6:7], 7, v[6:7]
	v_lshl_add_u64 v[6:7], s[0:1], 0, v[6:7]
	v_lshl_add_u64 v[6:7], v[6:7], 0, v[0:1]
	v_lshl_add_u64 v[8:9], v[4:5], 0, s[16:17]
	v_lshl_add_u64 v[8:9], v[8:9], 0, v[0:1]
	global_load_dwordx4 v[106:109], v[6:7], off
	global_load_dwordx4 v[110:113], v[8:9], off
	s_waitcnt vmcnt(3)
	ds_write_b128 v188, v[98:101]
	s_waitcnt vmcnt(2)
	ds_write2_b64 v192, v[102:103], v[104:105] offset1:1
	s_waitcnt vmcnt(1)
	ds_write_b128 v189, v[106:109]
	s_waitcnt vmcnt(0)
	ds_write2_b64 v191, v[110:111], v[112:113] offset1:1
	s_cmp_ge_i32 s6, s8
	s_cbranch_scc1 .LBB0_925
